# far loop: LDS-DMA issue moved from the loop top into MFMA gaps
# baseline (speedup 1.0000x reference)
; #define MFMA32(a, b, c) __builtin_amdgcn_mfma_f32_32x32x16_bf16((a), (b), (c), 0, 0, 0)
; #define AT_LOADK(t) do { AT_DMA(kg[0] + (size_t)(t) * 65536, ldsl + ((t) & 1) * AT_KS + dw); AT_DMA(kg[1] + (size_t)(t) * 65536, ldsl + ((t) & 1) * AT_KS + dw + 1024); } while (0)
; #define AT_LOADV(t) do { AT_DMA(vg[0] + (t) * 64, ldsl + AT_V0 + ((t) & 1) * AT_KS + dw); AT_DMA(vg[1] + (t) * 64, ldsl + AT_V0 + ((t) & 1) * AT_KS + dw + 1024); } while (0)
; DI void attn_pv(f32x16& s0, f32x16& s1, ldsp_t vb, const int* vro, f32x16* o, float& lsum) {
; #pragma unroll
;     for (int k = 0; k < 16; ++k) { s0[k] = __builtin_amdgcn_exp2f(s0[k]); s1[k] = __builtin_amdgcn_exp2f(s1[k]); }
;     float ps = 0.f;
; #pragma unroll
;     for (int k = 0; k < 16; ++k) ps += s0[k] + s1[k];
;     lsum += ps;
;     bf16x8 pk[4]; pk[0] = pack8(s0, 0); pk[1] = pack8(s0, 1); pk[2] = pack8(s1, 0); pk[3] = pack8(s1, 1);
; #pragma unroll
;     for (int kk = 0; kk < 4; ++kk)
; #pragma unroll
;         for (int et = 0; et < 4; ++et) {
;             const bf16x8 a = *(const __attribute__((address_space(3))) bf16x8*)(vb + vro[kk] + et * 4096);
;             o[et] = MFMA32(a, pk[kk], o[et]);
;         }
; }
; DI void attn_mfma_phase(PP P, int l, unsigned char* lds, int G, int cid) {
;     ...
;         for (; kt < nfar; ++kt) {
;             AT_LOADK(kt + 2); AT_LOADV(kt + 1);
;             attn_qk<false>(sn0, sn1, ldsl + ((kt + 1) & 1) * AT_KS, kro, qf, 0, tb2, hi, qg, r32);
;             attn_pv(sc0, sc1, ldsl + (kt & 1) * AT_KS, vro, o, lsum);
;             sc0 = sn0; sc1 = sn1;
;             __syncthreads();
;         }
.LBB0_213:
	s_add_i32 s7, s6, 0xffffc000
	s_and_b32 s7, s7, 0xc000
	s_and_b32 s10, s6, 0xc000
	v_add_u32_e32 v248, s7, v222
	v_add_u32_e32 v249, s7, v223
	s_add_i32 s11, s6, 0x8000
	s_and_b32 s11, s11, 0xc000
	s_add_i32 s11, s11, s65
	ds_read_b128 v[2:5], v248 offset:32768
	ds_read_b128 v[6:9], v248 offset:36864
	ds_read_b128 v[136:139], v248 offset:40960
	ds_read_b128 v[140:143], v248 offset:45056
	ds_read_b128 v[240:243], v249 offset:32768
	s_lshl_b64 s[8:9], s[20:21], 1
	v_add_u32_e32 v252, s10, v171
	v_add_u32_e32 v253, s10, v200
	v_add_u32_e32 v233, s10, v201
	v_add_u32_e32 v234, s10, v202
	v_add_u32_e32 v250, s7, v224
	v_add_u32_e32 v251, s7, v225
	v_add_f32_e32 v189, v189, v235
	s_addk_i32 s6, 0x4000
	s_add_i32 s20, s20, 64
	v_exp_f32_e32 v14, v104
	v_exp_f32_e32 v15, v105
	v_exp_f32_e32 v168, v106
	v_exp_f32_e32 v169, v107
	v_exp_f32_e32 v198, v108
	v_exp_f32_e32 v199, v109
	v_exp_f32_e32 v238, v110
	v_exp_f32_e32 v239, v111
	s_waitcnt lgkmcnt(4)
	v_mfma_f32_32x32x16_bf16 v[64:79], v[2:5], v[128:131], v[64:79]
	ds_read_b128 v[244:247], v249 offset:36864
	v_cvt_pk_bf16_f32 v132, v14, v15
	v_cvt_pk_bf16_f32 v133, v168, v169
	v_add_f32_e32 v14, v14, v15
	v_add_f32_e32 v168, v168, v169
	s_waitcnt lgkmcnt(4)
	v_mfma_f32_32x32x16_bf16 v[48:63], v[6:9], v[128:131], v[48:63]
	ds_read_b128 v[2:5], v249 offset:40960
	v_cvt_pk_bf16_f32 v134, v198, v199
	v_cvt_pk_bf16_f32 v135, v238, v239
	v_add_f32_e32 v198, v198, v199
	v_add_f32_e32 v238, v238, v239
	s_waitcnt lgkmcnt(4)
	v_mfma_f32_32x32x16_bf16 v[32:47], v[136:139], v[128:131], v[32:47]
	ds_read_b128 v[6:9], v249 offset:45056
	v_add_f32_e32 v14, v14, v168
	v_add_f32_e32 v198, v198, v238
	v_add_f32_e32 v14, v14, v198
	v_add_f32_e32 v189, v189, v14
	s_waitcnt lgkmcnt(4)
	v_mfma_f32_32x32x16_bf16 v[16:31], v[140:143], v[128:131], v[16:31]
	ds_read_b128 v[136:139], v252
	v_exp_f32_e32 v14, v80
	v_exp_f32_e32 v15, v81
	v_exp_f32_e32 v168, v82
	s_waitcnt lgkmcnt(4)
	v_mfma_f32_32x32x16_bf16 v[64:79], v[240:243], v[132:135], v[64:79]
	ds_read_b128 v[140:143], v253
	s_add_i32 m0, s7, s64
	v_exp_f32_e32 v169, v83
	v_exp_f32_e32 v198, v84
	v_exp_f32_e32 v199, v85
	global_load_lds_dwordx4 v[12:13], off
	s_waitcnt lgkmcnt(4)
	v_mfma_f32_32x32x16_bf16 v[48:63], v[244:247], v[132:135], v[48:63]
	ds_read_b128 v[240:243], v233
	s_add_i32 m0, m0, 0x400
	v_lshl_add_u64 v[236:237], v[194:195], 0, s[8:9]
	v_exp_f32_e32 v238, v86
	v_exp_f32_e32 v239, v87
	v_cvt_pk_bf16_f32 v128, v14, v15
	global_load_lds_dwordx4 v[10:11], off
	s_waitcnt lgkmcnt(4)
	v_mfma_f32_32x32x16_bf16 v[32:47], v[2:5], v[132:135], v[32:47]
	ds_read_b128 v[244:247], v234
	s_add_i32 m0, s11, 0x10000
	v_cvt_pk_bf16_f32 v129, v168, v169
	v_add_f32_e32 v14, v14, v15
	v_add_f32_e32 v168, v168, v169
	global_load_lds_dwordx4 v[236:237], off
	v_lshl_add_u64 v[236:237], v[196:197], 0, s[8:9]
	s_waitcnt lgkmcnt(4)
	v_mfma_f32_32x32x16_bf16 v[16:31], v[6:9], v[132:135], v[16:31]
	ds_read_b128 v[2:5], v250 offset:32768
	s_add_i32 m0, s11, 0x10400
	v_cvt_pk_bf16_f32 v130, v198, v199
	v_cvt_pk_bf16_f32 v131, v238, v239
	v_add_f32_e32 v198, v198, v199
	global_load_lds_dwordx4 v[236:237], off
	s_waitcnt lgkmcnt(4)
	v_mfma_f32_32x32x16_bf16 v[96:111], v[136:139], v[156:159], v[112:127]
	ds_read_b128 v[6:9], v250 offset:36864
	v_add_f32_e32 v238, v238, v239
	v_add_f32_e32 v14, v14, v168
	v_add_f32_e32 v198, v198, v238
	s_waitcnt lgkmcnt(4)
	v_mfma_f32_32x32x16_bf16 v[96:111], v[140:143], v[152:155], v[96:111]
	ds_read_b128 v[136:139], v250 offset:40960
	v_add_f32_e32 v14, v14, v198
	v_add_f32_e32 v189, v189, v14
	s_waitcnt lgkmcnt(4)
	v_mfma_f32_32x32x16_bf16 v[96:111], v[240:243], v[148:151], v[96:111]
	ds_read_b128 v[140:143], v250 offset:45056
	v_exp_f32_e32 v14, v88
	v_exp_f32_e32 v15, v89
	v_exp_f32_e32 v168, v90
	s_waitcnt lgkmcnt(4)
	v_mfma_f32_32x32x16_bf16 v[96:111], v[244:247], v[144:147], v[96:111]
	ds_read_b128 v[240:243], v251 offset:32768
	v_exp_f32_e32 v169, v91
	v_exp_f32_e32 v198, v92
	v_exp_f32_e32 v199, v93
	s_waitcnt lgkmcnt(4)
	v_mfma_f32_32x32x16_bf16 v[64:79], v[2:5], v[128:131], v[64:79]
	ds_read_b128 v[244:247], v251 offset:36864
	v_exp_f32_e32 v238, v94
	v_exp_f32_e32 v239, v95
	v_cvt_pk_bf16_f32 v132, v14, v15
	v_cvt_pk_bf16_f32 v133, v168, v169
	s_waitcnt lgkmcnt(4)
	v_mfma_f32_32x32x16_bf16 v[48:63], v[6:9], v[128:131], v[48:63]
	ds_read_b128 v[2:5], v251 offset:40960
	v_add_f32_e32 v14, v14, v15
	v_add_f32_e32 v168, v168, v169
	v_cvt_pk_bf16_f32 v134, v198, v199
	v_cvt_pk_bf16_f32 v135, v238, v239
	s_waitcnt lgkmcnt(4)
	v_mfma_f32_32x32x16_bf16 v[32:47], v[136:139], v[128:131], v[32:47]
	ds_read_b128 v[6:9], v251 offset:45056
	v_add_f32_e32 v198, v198, v199
	v_add_f32_e32 v238, v238, v239
	v_add_f32_e32 v14, v14, v168
	s_waitcnt lgkmcnt(4)
	v_mfma_f32_32x32x16_bf16 v[16:31], v[140:143], v[128:131], v[16:31]
	ds_read_b128 v[136:139], v252 offset:8192
	v_add_f32_e32 v198, v198, v238
	v_add_f32_e32 v14, v14, v198
	v_add_f32_e32 v189, v189, v14
	s_waitcnt lgkmcnt(4)
	v_mfma_f32_32x32x16_bf16 v[64:79], v[240:243], v[132:135], v[64:79]
	ds_read_b128 v[140:143], v253 offset:8192
	v_exp_f32_e32 v14, v96
	v_exp_f32_e32 v15, v97
	v_exp_f32_e32 v168, v98
	s_waitcnt lgkmcnt(4)
	v_mfma_f32_32x32x16_bf16 v[48:63], v[244:247], v[132:135], v[48:63]
	ds_read_b128 v[240:243], v233 offset:8192
	v_exp_f32_e32 v169, v99
	v_exp_f32_e32 v198, v100
	v_exp_f32_e32 v199, v101
	s_waitcnt lgkmcnt(4)
	v_mfma_f32_32x32x16_bf16 v[32:47], v[2:5], v[132:135], v[32:47]
	ds_read_b128 v[244:247], v234 offset:8192
	v_exp_f32_e32 v238, v102
	v_exp_f32_e32 v239, v103
	v_cvt_pk_bf16_f32 v128, v14, v15
	s_waitcnt lgkmcnt(4)
	v_mfma_f32_32x32x16_bf16 v[16:31], v[6:9], v[132:135], v[16:31]
	v_cvt_pk_bf16_f32 v129, v168, v169
	v_cvt_pk_bf16_f32 v130, v198, v199
	v_cvt_pk_bf16_f32 v131, v238, v239
	s_waitcnt lgkmcnt(3)
	v_mfma_f32_32x32x16_bf16 v[80:95], v[136:139], v[156:159], v[112:127]
	v_add_f32_e32 v14, v14, v15
	v_add_f32_e32 v168, v168, v169
	v_add_f32_e32 v198, v198, v199
	v_add_f32_e32 v238, v238, v239
	s_waitcnt lgkmcnt(2)
	v_mfma_f32_32x32x16_bf16 v[80:95], v[140:143], v[152:155], v[80:95]
	v_add_f32_e32 v14, v14, v168
	v_add_f32_e32 v198, v198, v238
	v_add_f32_e32 v235, v14, v198
	v_add_co_u32_e32 v232, vcc, 1, v232
	s_waitcnt vmcnt(8) lgkmcnt(0)
	s_barrier
; #define AT_LOADK(t) do { AT_DMA(kg[0] + (size_t)(t) * 65536, ldsl + ((t) & 1) * AT_KS + dw); AT_DMA(kg[1] + (size_t)(t) * 65536, ldsl + ((t) & 1) * AT_KS + dw + 1024); } while (0)
; #define AT_LOADV(t) do { AT_DMA(vg[0] + (t) * 64, ldsl + AT_V0 + ((t) & 1) * AT_KS + dw); AT_DMA(vg[1] + (t) * 64, ldsl + AT_V0 + ((t) & 1) * AT_KS + dw + 1024); } while (0)
; DI void attn_mfma_phase(PP P, int l, unsigned char* lds, int G, int cid) {
;     ...
;         for (; kt < nfar; ++kt) {
;             AT_LOADK(kt + 2); AT_LOADV(kt + 1);
;             attn_qk<false>(sn0, sn1, ldsl + ((kt + 1) & 1) * AT_KS, kro, qf, 0, tb2, hi, qg, r32);
;             attn_pv(sc0, sc1, ldsl + (kt & 1) * AT_KS, vro, o, lsum);
;             sc0 = sn0; sc1 = sn1;
;             __syncthreads();
;         }
;         for (; kt < 2 * j; ++kt) {
	v_mfma_f32_32x32x16_bf16 v[80:95], v[240:243], v[148:151], v[80:95]
	v_lshl_add_u64 v[12:13], v[12:13], 0, s[34:35]
	v_lshl_add_u64 v[10:11], v[10:11], 0, s[34:35]
	s_and_b64 vcc, exec, vcc
	v_mfma_f32_32x32x16_bf16 v[80:95], v[244:247], v[144:147], v[80:95]
	s_cbranch_vccz .LBB0_213
	s_nop 11
	v_mov_b64_e32 v[142:143], v[94:95]
	v_mov_b64_e32 v[126:127], v[110:111]
	v_mov_b64_e32 v[140:141], v[92:93]
	v_mov_b64_e32 v[138:139], v[90:91]
	v_mov_b64_e32 v[136:137], v[88:89]
	v_mov_b64_e32 v[134:135], v[86:87]
	v_mov_b64_e32 v[132:133], v[84:85]
	v_mov_b64_e32 v[130:131], v[82:83]
	v_mov_b64_e32 v[128:129], v[80:81]
	v_mov_b64_e32 v[124:125], v[108:109]
	v_mov_b64_e32 v[122:123], v[106:107]
	v_mov_b64_e32 v[120:121], v[104:105]
	v_mov_b64_e32 v[118:119], v[102:103]
	v_mov_b64_e32 v[116:117], v[100:101]
	v_mov_b64_e32 v[114:115], v[98:99]
	v_mov_b64_e32 v[112:113], v[96:97]
	s_lshl_b32 s83, s39, 7
	s_cmp_ge_i32 s38, s13
	s_cbranch_scc0 .LBB0_216
	s_branch .LBB0_219
